# out-proj GEMM K-loop rewritten: next K-step loads issued right after the LDS publish barrier (scalar bases + lane offsets), single-buffered fragments
# speedup vs baseline: 1.1078x; 1.0034x over previous
; DEV f32x16 mfma32(bf16x8 a, bf16x8 b, f32x16 c) { return __builtin_amdgcn_mfma_f32_32x32x16_bf16(a, b, c, 0, 0, 0); }
; template <int EPI>
; __device__ void gemm_phase256(const Params& P, int l, const bf16_t* __restrict__ A, const bf16_t* __restrict__ Bt, int NT, char* smem) {
;     ...
;     for (int kt = 0; kt < 16; ++kt) {
;       __syncthreads();
;       {
;         bf16_t* as = As + lrow * 72 + lc8; bf16_t* bs = Bs + lrow * 72 + lc8;
;         *(uint4*)(as) = ra0; *(uint4*)(as + 32 * 72) = ra1; *(uint4*)(as + 64 * 72) = ra2; *(uint4*)(as + 96 * 72) = ra3;
;         *(uint4*)(as + 128 * 72) = ra4; *(uint4*)(as + 160 * 72) = ra5; *(uint4*)(as + 192 * 72) = ra6; *(uint4*)(as + 224 * 72) = ra7;
;         *(uint4*)(bs) = rb0; *(uint4*)(bs + 32 * 72) = rb1; *(uint4*)(bs + 64 * 72) = rb2; *(uint4*)(bs + 96 * 72) = rb3;
;       }
;       __syncthreads();
;       {
;         const int k0 = (kt + 1 < 16) ? (kt + 1) * 64 : 15 * 64;
;         GLOAD2(k0);
;       }
; #pragma unroll
;       for (int kk = 0; kk < 4; ++kk) {
;         bf16x8 af[4], bfr[2];
; #pragma unroll
;         for (int mi = 0; mi < 4; ++mi) af[mi] = *(const bf16x8*)(As + (wm * 128 + mi * 32 + lr) * 72 + kk * 16 + hk * 8);
; #pragma unroll
;         for (int ni = 0; ni < 2; ++ni) bfr[ni] = *(const bf16x8*)(Bs + (wn * 64 + ni * 32 + lr) * 72 + kk * 16 + hk * 8);
; #pragma unroll
;         for (int mi = 0; mi < 4; ++mi)
; #pragma unroll
;           for (int ni = 0; ni < 2; ++ni) acc[mi][ni] = mfma32(af[mi], bfr[ni], acc[mi][ni]);
;       }
.LBB0_104:
	s_mov_b32 s37, s0
	v_readfirstlane_b32 s40, v196
	v_readfirstlane_b32 s41, v197
	v_readfirstlane_b32 s0, v198
	v_readfirstlane_b32 s1, v199
	s_nop 1
	v_subrev_u32_e32 v182, s40, v196
	v_add_u32_e32 v226, 0x10000, v182
	v_add_u32_e32 v227, 0x20000, v182
	v_add_u32_e32 v254, 0x30000, v182
	s_add_u32 s40, s40, 0x80
	s_addc_u32 s41, s41, 0
	s_add_u32 s0, s0, 0x80
	s_addc_u32 s1, s1, 0
	s_add_u32 s42, s40, 0x40000
	s_addc_u32 s43, s41, 0
	s_mov_b32 s7, 0
.Lgemm_out_loop:
	s_barrier
	s_waitcnt vmcnt(11)
	ds_write_b128 v188, v[128:131]
	s_waitcnt vmcnt(10)
	ds_write_b128 v188, v[132:135] offset:4608
	s_waitcnt vmcnt(9)
	ds_write_b128 v188, v[140:143] offset:9216
	s_waitcnt vmcnt(8)
	ds_write_b128 v188, v[144:147] offset:13824
	s_waitcnt vmcnt(7)
	ds_write_b128 v188, v[148:151] offset:18432
	s_waitcnt vmcnt(6)
	ds_write_b128 v188, v[152:155] offset:23040
	s_waitcnt vmcnt(5)
	ds_write_b128 v188, v[156:159] offset:27648
	s_waitcnt vmcnt(4)
	ds_write_b128 v188, v[160:163] offset:32256
	s_waitcnt vmcnt(3)
	ds_write_b128 v188, v[136:139] offset:36864
	s_waitcnt vmcnt(2)
	ds_write_b128 v188, v[164:167] offset:41472
	s_waitcnt vmcnt(1)
	ds_write_b128 v188, v[168:171] offset:46080
	s_waitcnt vmcnt(0)
	ds_write_b128 v188, v[172:175] offset:50688
	s_waitcnt lgkmcnt(0)
	s_barrier
	global_load_dwordx4 v[128:131], v182, s[40:41]
	global_load_dwordx4 v[132:135], v226, s[40:41]
	global_load_dwordx4 v[140:143], v227, s[40:41]
	global_load_dwordx4 v[144:147], v254, s[40:41]
	global_load_dwordx4 v[148:151], v182, s[42:43]
	global_load_dwordx4 v[152:155], v226, s[42:43]
	global_load_dwordx4 v[156:159], v227, s[42:43]
	global_load_dwordx4 v[160:163], v254, s[42:43]
	global_load_dwordx4 v[136:139], v182, s[0:1]
	global_load_dwordx4 v[164:167], v226, s[0:1]
	global_load_dwordx4 v[168:171], v227, s[0:1]
	global_load_dwordx4 v[172:175], v254, s[0:1]
	s_add_u32 s40, s40, 0x80
	s_addc_u32 s41, s41, 0
	s_add_u32 s42, s42, 0x80
	s_addc_u32 s43, s43, 0
	s_add_u32 s0, s0, 0x80
	s_addc_u32 s1, s1, 0
	ds_read_b128 v[244:247], v201 offset:36864
	ds_read_b128 v[228:231], v191
	ds_read_b128 v[232:235], v191 offset:4608
	ds_read_b128 v[196:199], v201 offset:41472
	ds_read_b128 v[236:239], v191 offset:9216
	ds_read_b128 v[240:243], v200
	s_waitcnt lgkmcnt(4)
	v_mfma_f32_32x32x16_bf16 v[112:127], v[228:231], v[244:247], v[112:127]
	s_waitcnt lgkmcnt(3)
	v_mfma_f32_32x32x16_bf16 v[80:95], v[232:235], v[244:247], v[80:95]
	s_waitcnt lgkmcnt(1)
	v_mfma_f32_32x32x16_bf16 v[48:63], v[236:239], v[244:247], v[48:63]
	s_waitcnt lgkmcnt(0)
	v_mfma_f32_32x32x16_bf16 v[16:31], v[240:243], v[244:247], v[16:31]
	ds_read_b128 v[244:247], v201 offset:36896
	s_waitcnt lgkmcnt(3)
	v_mfma_f32_32x32x16_bf16 v[96:111], v[228:231], v[196:199], v[96:111]
	ds_read_b128 v[228:231], v191 offset:32
	s_waitcnt lgkmcnt(4)
	v_mfma_f32_32x32x16_bf16 v[64:79], v[232:235], v[196:199], v[64:79]
	ds_read_b128 v[232:235], v191 offset:4640
	s_waitcnt lgkmcnt(4)
	v_mfma_f32_32x32x16_bf16 v[32:47], v[236:239], v[196:199], v[32:47]
	ds_read_b128 v[236:239], v191 offset:9248
	s_waitcnt lgkmcnt(4)
	v_mfma_f32_32x32x16_bf16 v[0:15], v[240:243], v[196:199], v[0:15]
	ds_read_b128 v[240:243], v200 offset:32
	ds_read_b128 v[196:199], v201 offset:41504
	s_waitcnt lgkmcnt(4)
	v_mfma_f32_32x32x16_bf16 v[112:127], v[228:231], v[244:247], v[112:127]
	s_waitcnt lgkmcnt(3)
	v_mfma_f32_32x32x16_bf16 v[80:95], v[232:235], v[244:247], v[80:95]
	s_waitcnt lgkmcnt(2)
	v_mfma_f32_32x32x16_bf16 v[48:63], v[236:239], v[244:247], v[48:63]
	s_waitcnt lgkmcnt(1)
	v_mfma_f32_32x32x16_bf16 v[16:31], v[240:243], v[244:247], v[16:31]
	ds_read_b128 v[244:247], v201 offset:36928
	s_waitcnt lgkmcnt(1)
	v_mfma_f32_32x32x16_bf16 v[96:111], v[228:231], v[196:199], v[96:111]
	ds_read_b128 v[228:231], v191 offset:64
	s_waitcnt lgkmcnt(2)
	v_mfma_f32_32x32x16_bf16 v[64:79], v[232:235], v[196:199], v[64:79]
	ds_read_b128 v[232:235], v191 offset:4672
	s_waitcnt lgkmcnt(3)
	v_mfma_f32_32x32x16_bf16 v[32:47], v[236:239], v[196:199], v[32:47]
	ds_read_b128 v[236:239], v191 offset:9280
	s_waitcnt lgkmcnt(4)
	v_mfma_f32_32x32x16_bf16 v[0:15], v[240:243], v[196:199], v[0:15]
	ds_read_b128 v[240:243], v200 offset:64
	ds_read_b128 v[196:199], v201 offset:41536
	s_waitcnt lgkmcnt(4)
	v_mfma_f32_32x32x16_bf16 v[112:127], v[228:231], v[244:247], v[112:127]
	s_waitcnt lgkmcnt(3)
	v_mfma_f32_32x32x16_bf16 v[80:95], v[232:235], v[244:247], v[80:95]
	s_waitcnt lgkmcnt(2)
	v_mfma_f32_32x32x16_bf16 v[48:63], v[236:239], v[244:247], v[48:63]
	s_waitcnt lgkmcnt(1)
	v_mfma_f32_32x32x16_bf16 v[16:31], v[240:243], v[244:247], v[16:31]
	ds_read_b128 v[244:247], v201 offset:36960
	s_waitcnt lgkmcnt(1)
	v_mfma_f32_32x32x16_bf16 v[96:111], v[228:231], v[196:199], v[96:111]
	ds_read_b128 v[228:231], v191 offset:96
	s_waitcnt lgkmcnt(2)
	v_mfma_f32_32x32x16_bf16 v[64:79], v[232:235], v[196:199], v[64:79]
	ds_read_b128 v[232:235], v191 offset:4704
	s_waitcnt lgkmcnt(3)
	v_mfma_f32_32x32x16_bf16 v[32:47], v[236:239], v[196:199], v[32:47]
	ds_read_b128 v[236:239], v191 offset:9312
	s_waitcnt lgkmcnt(4)
	v_mfma_f32_32x32x16_bf16 v[0:15], v[240:243], v[196:199], v[0:15]
	ds_read_b128 v[240:243], v200 offset:96
	ds_read_b128 v[196:199], v201 offset:41568
	s_waitcnt lgkmcnt(4)
	v_mfma_f32_32x32x16_bf16 v[112:127], v[228:231], v[244:247], v[112:127]
	s_waitcnt lgkmcnt(3)
	v_mfma_f32_32x32x16_bf16 v[80:95], v[232:235], v[244:247], v[80:95]
	s_waitcnt lgkmcnt(2)
	v_mfma_f32_32x32x16_bf16 v[48:63], v[236:239], v[244:247], v[48:63]
	s_waitcnt lgkmcnt(1)
	v_mfma_f32_32x32x16_bf16 v[16:31], v[240:243], v[244:247], v[16:31]
	s_waitcnt lgkmcnt(0)
	v_mfma_f32_32x32x16_bf16 v[96:111], v[228:231], v[196:199], v[96:111]
	s_waitcnt lgkmcnt(0)
	v_mfma_f32_32x32x16_bf16 v[64:79], v[232:235], v[196:199], v[64:79]
	s_waitcnt lgkmcnt(0)
	v_mfma_f32_32x32x16_bf16 v[32:47], v[236:239], v[196:199], v[32:47]
	s_waitcnt lgkmcnt(0)
	v_mfma_f32_32x32x16_bf16 v[0:15], v[240:243], v[196:199], v[0:15]
	s_add_i32 s7, s7, 1
	s_cmp_eq_u32 s7, 15
	s_cbranch_scc0 .Lgemm_out_loop
; DEV unsigned short f2bf(float f) { return (unsigned short)(pack2(f, 0.f) & 0xFFFFu); }
; DEV f32x16 mfma32(bf16x8 a, bf16x8 b, f32x16 c) { return __builtin_amdgcn_mfma_f32_32x32x16_bf16(a, b, c, 0, 0, 0); }
; template <int EPI>
; __device__ void gemm_phase256(const Params& P, int l, const bf16_t* __restrict__ A, const bf16_t* __restrict__ Bt, int NT, char* smem) {
;     ...
;         *(uint4*)(as) = ra0; *(uint4*)(as + 32 * 72) = ra1; *(uint4*)(as + 64 * 72) = ra2; *(uint4*)(as + 96 * 72) = ra3;
;         *(uint4*)(as + 128 * 72) = ra4; *(uint4*)(as + 160 * 72) = ra5; *(uint4*)(as + 192 * 72) = ra6; *(uint4*)(as + 224 * 72) = ra7;
;         *(uint4*)(bs) = rb0; *(uint4*)(bs + 32 * 72) = rb1; *(uint4*)(bs + 64 * 72) = rb2; *(uint4*)(bs + 96 * 72) = rb3;
;       }
;       __syncthreads();
;       {
;         const int k0 = (kt + 1 < 16) ? (kt + 1) * 64 : 15 * 64;
;         GLOAD2(k0);
;       }
; #pragma unroll
;       for (int kk = 0; kk < 4; ++kk) {
;         bf16x8 af[4], bfr[2];
; #pragma unroll
;         for (int mi = 0; mi < 4; ++mi) af[mi] = *(const bf16x8*)(As + (wm * 128 + mi * 32 + lr) * 72 + kk * 16 + hk * 8);
; #pragma unroll
;         for (int ni = 0; ni < 2; ++ni) bfr[ni] = *(const bf16x8*)(Bs + (wn * 64 + ni * 32 + lr) * 72 + kk * 16 + hk * 8);
; #pragma unroll
;         for (int mi = 0; mi < 4; ++mi)
; #pragma unroll
;           for (int ni = 0; ni < 2; ++ni) acc[mi][ni] = mfma32(af[mi], bfr[ni], acc[mi][ni]);
;     ...
; #pragma unroll
;       for (int mi = 0; mi < 4; ++mi)
; #pragma unroll
;         for (int ni = 0; ni < 2; ++ni) {
;           const int col = wn * 64 + ni * 32 + lr;
;           const int n = n0 + col;
;           const float bias = (EPI == 0) ? ((n < NIN) ? P.b_in[l * NIN + n] : 0.f) : 0.f;
;           const int rb = wm * 128 + mi * 32 + 4 * hk;
; #pragma unroll
;           for (int i = 0; i < 16; ++i) Cs[(rb + (i & 3) + 8 * (i >> 2)) * 136 + col] = f2bf(acc[mi][ni][i] + bias);
	s_waitcnt vmcnt(0)
	s_mov_b32 s0, s37
	s_barrier
	s_waitcnt vmcnt(10)
	ds_write_b128 v188, v[128:131]
	s_waitcnt vmcnt(9)
	ds_write_b128 v188, v[132:135] offset:4608
	s_waitcnt vmcnt(8)
	ds_write_b128 v188, v[140:143] offset:9216
	s_waitcnt vmcnt(7)
	ds_write_b128 v188, v[144:147] offset:13824
	s_waitcnt vmcnt(6)
	ds_write_b128 v188, v[148:151] offset:18432
	s_waitcnt vmcnt(5)
	ds_write_b128 v188, v[152:155] offset:23040
	s_waitcnt vmcnt(4)
	ds_write_b128 v188, v[156:159] offset:27648
	s_waitcnt vmcnt(3)
	ds_write_b128 v188, v[160:163] offset:32256
	ds_write_b128 v188, v[136:139] offset:36864
	s_waitcnt vmcnt(2)
	ds_write_b128 v188, v[164:167] offset:41472
	s_waitcnt vmcnt(1)
	ds_write_b128 v188, v[168:171] offset:46080
	s_waitcnt vmcnt(0)
	ds_write_b128 v188, v[172:175] offset:50688
	s_waitcnt lgkmcnt(0)
	s_barrier
	ds_read_b128 v[128:131], v191 offset:4608
	ds_read_b128 v[132:135], v191 offset:9216
	ds_read_b128 v[136:139], v201 offset:41472
	ds_read_b128 v[140:143], v191
	ds_read_b128 v[144:147], v191 offset:32
	ds_read_b128 v[148:151], v201 offset:36864
	ds_read_b128 v[152:155], v201 offset:36896
	s_waitcnt lgkmcnt(1)
	v_mfma_f32_32x32x16_bf16 v[80:95], v[128:131], v[148:151], v[80:95]
	s_ashr_i32 s1, s0, 31
	v_mfma_f32_32x32x16_bf16 v[64:79], v[128:131], v[136:139], v[64:79]
	v_mfma_f32_32x32x16_bf16 v[48:63], v[132:135], v[148:151], v[48:63]
	v_mfma_f32_32x32x16_bf16 v[32:47], v[132:135], v[136:139], v[32:47]
	ds_read_b128 v[128:131], v200
	ds_read_b128 v[132:135], v200 offset:32
	s_waitcnt lgkmcnt(1)
	v_mfma_f32_32x32x16_bf16 v[0:15], v[128:131], v[136:139], v[0:15]
	v_mfma_f32_32x32x16_bf16 v[112:127], v[140:143], v[148:151], v[112:127]
	v_mfma_f32_32x32x16_bf16 v[96:111], v[140:143], v[136:139], v[96:111]
	v_mfma_f32_32x32x16_bf16 v[16:31], v[128:131], v[148:151], v[16:31]
	ds_read_b128 v[128:131], v191 offset:4640
	ds_read_b128 v[136:139], v191 offset:9248
	ds_read_b128 v[140:143], v201 offset:41504
	s_waitcnt lgkmcnt(0)
	v_mfma_f32_32x32x16_bf16 v[0:15], v[132:135], v[140:143], v[0:15]
	v_mfma_f32_32x32x16_bf16 v[112:127], v[144:147], v[152:155], v[112:127]
	v_mfma_f32_32x32x16_bf16 v[96:111], v[144:147], v[140:143], v[96:111]
	v_mfma_f32_32x32x16_bf16 v[80:95], v[128:131], v[152:155], v[80:95]
	v_mfma_f32_32x32x16_bf16 v[64:79], v[128:131], v[140:143], v[64:79]
	v_mfma_f32_32x32x16_bf16 v[48:63], v[136:139], v[152:155], v[48:63]
	v_mfma_f32_32x32x16_bf16 v[32:47], v[136:139], v[140:143], v[32:47]
	v_mfma_f32_32x32x16_bf16 v[16:31], v[132:135], v[152:155], v[16:31]
	ds_read_b128 v[128:131], v191 offset:64
	ds_read_b128 v[132:135], v191 offset:4672
	ds_read_b128 v[136:139], v191 offset:9280
	ds_read_b128 v[140:143], v200 offset:64
	ds_read_b128 v[144:147], v201 offset:36928
	ds_read_b128 v[148:151], v201 offset:41536
	s_waitcnt lgkmcnt(0)
	v_mfma_f32_32x32x16_bf16 v[0:15], v[140:143], v[148:151], v[0:15]
	v_mfma_f32_32x32x16_bf16 v[112:127], v[128:131], v[144:147], v[112:127]
	v_mfma_f32_32x32x16_bf16 v[96:111], v[128:131], v[148:151], v[96:111]
	v_mfma_f32_32x32x16_bf16 v[80:95], v[132:135], v[144:147], v[80:95]
	v_mfma_f32_32x32x16_bf16 v[64:79], v[132:135], v[148:151], v[64:79]
	v_mfma_f32_32x32x16_bf16 v[48:63], v[136:139], v[144:147], v[48:63]
	v_mfma_f32_32x32x16_bf16 v[32:47], v[136:139], v[148:151], v[32:47]
	v_mfma_f32_32x32x16_bf16 v[16:31], v[140:143], v[144:147], v[16:31]
	ds_read_b128 v[128:131], v191 offset:96
	ds_read_b128 v[132:135], v191 offset:4704
	ds_read_b128 v[136:139], v191 offset:9312
	ds_read_b128 v[140:143], v200 offset:96
	ds_read_b128 v[144:147], v201 offset:36960
	ds_read_b128 v[148:151], v201 offset:41568
	s_waitcnt lgkmcnt(0)
	s_barrier
	v_mfma_f32_32x32x16_bf16 v[0:15], v[140:143], v[148:151], v[0:15]
	v_mfma_f32_32x32x16_bf16 v[112:127], v[128:131], v[144:147], v[112:127]
	s_nop 10
	v_add_f32_e32 v0, 0, v0
	v_cvt_pk_bf16_f32 v0, v0, s0
	ds_write_b16 v190, v0 offset:26176
	v_add_f32_e32 v0, 0, v1
	v_cvt_pk_bf16_f32 v0, v0, s0
	ds_write_b16 v190, v0 offset:26448
	v_add_f32_e32 v0, 0, v2
	v_mfma_f32_32x32x16_bf16 v[96:111], v[128:131], v[148:151], v[96:111]
	v_add_f32_e32 v112, 0, v112
	v_cvt_pk_bf16_f32 v112, v112, s0
	ds_write_b16 v190, v112
	v_add_f32_e32 v112, 0, v113
	v_cvt_pk_bf16_f32 v112, v112, s0
	ds_write_b16 v190, v112 offset:272
	v_add_f32_e32 v112, 0, v114
	v_mfma_f32_32x32x16_bf16 v[80:95], v[132:135], v[144:147], v[80:95]
	s_nop 3
	v_add_f32_e32 v96, 0, v96
	v_cvt_pk_bf16_f32 v96, v96, s0
	ds_write_b16 v190, v96 offset:64
	v_add_f32_e32 v96, 0, v97
	v_cvt_pk_bf16_f32 v96, v96, s0
	ds_write_b16 v190, v96 offset:336
	v_add_f32_e32 v96, 0, v98
	v_mfma_f32_32x32x16_bf16 v[64:79], v[132:135], v[148:151], v[64:79]
	v_add_f32_e32 v80, 0, v80
	v_cvt_pk_bf16_f32 v80, v80, s0
	ds_write_b16 v190, v80 offset:8704
	v_add_f32_e32 v80, 0, v81
	v_cvt_pk_bf16_f32 v80, v80, s0
	ds_write_b16 v190, v80 offset:8976
	v_add_f32_e32 v80, 0, v82
	v_mfma_f32_32x32x16_bf16 v[48:63], v[136:139], v[144:147], v[48:63]
	s_nop 3
	v_add_f32_e32 v64, 0, v64
	v_cvt_pk_bf16_f32 v64, v64, s0
	ds_write_b16 v190, v64 offset:8768
	v_add_f32_e32 v64, 0, v65
	v_cvt_pk_bf16_f32 v64, v64, s0
	ds_write_b16 v190, v64 offset:9040
	v_add_f32_e32 v64, 0, v66
	v_mfma_f32_32x32x16_bf16 v[32:47], v[136:139], v[148:151], v[32:47]
	v_add_f32_e32 v48, 0, v48
	v_cvt_pk_bf16_f32 v48, v48, s0
	ds_write_b16 v190, v48 offset:17408
	v_add_f32_e32 v48, 0, v49
	v_cvt_pk_bf16_f32 v48, v48, s0
	ds_write_b16 v190, v48 offset:17680
	v_add_f32_e32 v48, 0, v50
	v_mfma_f32_32x32x16_bf16 v[16:31], v[140:143], v[144:147], v[16:31]
	s_nop 3
	v_add_f32_e32 v32, 0, v32
	v_cvt_pk_bf16_f32 v32, v32, s0
	ds_write_b16 v190, v32 offset:17472
	v_add_f32_e32 v32, 0, v33
; DEV unsigned short f2bf(float f) { return (unsigned short)(pack2(f, 0.f) & 0xFFFFu); }
; template <int EPI>
; __device__ void gemm_phase256(const Params& P, int l, const bf16_t* __restrict__ A, const bf16_t* __restrict__ Bt, int NT, char* smem) {
;     ...
; #pragma unroll
;       for (int mi = 0; mi < 4; ++mi)
; #pragma unroll
;         for (int ni = 0; ni < 2; ++ni) {
;           const int col = wn * 64 + ni * 32 + lr;
;           const int n = n0 + col;
;           const float bias = (EPI == 0) ? ((n < NIN) ? P.b_in[l * NIN + n] : 0.f) : 0.f;
;           const int rb = wm * 128 + mi * 32 + 4 * hk;
; #pragma unroll
;           for (int i = 0; i < 16; ++i) Cs[(rb + (i & 3) + 8 * (i >> 2)) * 136 + col] = f2bf(acc[mi][ni][i] + bias);
;         }
	v_cvt_pk_bf16_f32 v32, v32, s0
	ds_write_b16 v190, v32 offset:17744
	v_add_f32_e32 v32, 0, v34
	s_nop 0
	v_add_f32_e32 v16, 0, v16
	v_cvt_pk_bf16_f32 v16, v16, s0
	ds_write_b16 v190, v16 offset:26112
	v_add_f32_e32 v16, 0, v17
	v_cvt_pk_bf16_f32 v16, v16, s0
	ds_write_b16 v190, v16 offset:26384
	v_add_f32_e32 v16, 0, v18
	v_cvt_pk_bf16_f32 v0, v0, s0
	v_cvt_pk_bf16_f32 v112, v112, s0
	v_cvt_pk_bf16_f32 v96, v96, s0
	v_cvt_pk_bf16_f32 v80, v80, s0
	v_cvt_pk_bf16_f32 v64, v64, s0
	v_cvt_pk_bf16_f32 v48, v48, s0
	v_cvt_pk_bf16_f32 v32, v32, s0
	v_cvt_pk_bf16_f32 v16, v16, s0
	ds_write_b16 v190, v0 offset:26720
	v_add_f32_e32 v0, 0, v3
	ds_write_b16 v190, v112 offset:544
	v_add_f32_e32 v112, 0, v115
	ds_write_b16 v190, v96 offset:608
	v_add_f32_e32 v96, 0, v99
	ds_write_b16 v190, v80 offset:9248
	v_add_f32_e32 v80, 0, v83
	ds_write_b16 v190, v64 offset:9312
	v_add_f32_e32 v64, 0, v67
	ds_write_b16 v190, v48 offset:17952
	v_add_f32_e32 v48, 0, v51
	ds_write_b16 v190, v32 offset:18016
	v_add_f32_e32 v32, 0, v35
	ds_write_b16 v190, v16 offset:26656
	v_add_f32_e32 v16, 0, v19
	v_cvt_pk_bf16_f32 v0, v0, s0
	v_cvt_pk_bf16_f32 v112, v112, s0
	v_cvt_pk_bf16_f32 v96, v96, s0
	v_cvt_pk_bf16_f32 v80, v80, s0
	v_cvt_pk_bf16_f32 v64, v64, s0
	v_cvt_pk_bf16_f32 v48, v48, s0
	v_cvt_pk_bf16_f32 v32, v32, s0
	v_cvt_pk_bf16_f32 v16, v16, s0
	ds_write_b16 v190, v0 offset:26992
	v_add_f32_e32 v0, 0, v4
	ds_write_b16 v190, v112 offset:816
	v_add_f32_e32 v112, 0, v116
	ds_write_b16 v190, v96 offset:880
	v_add_f32_e32 v96, 0, v100
	ds_write_b16 v190, v80 offset:9520
	v_add_f32_e32 v80, 0, v84
	ds_write_b16 v190, v64 offset:9584
	v_add_f32_e32 v64, 0, v68
	ds_write_b16 v190, v48 offset:18224
	v_add_f32_e32 v48, 0, v52
	ds_write_b16 v190, v32 offset:18288
	v_add_f32_e32 v32, 0, v36
	ds_write_b16 v190, v16 offset:26928
	v_add_f32_e32 v16, 0, v20
	v_cvt_pk_bf16_f32 v0, v0, s0
	v_cvt_pk_bf16_f32 v112, v112, s0
	v_cvt_pk_bf16_f32 v96, v96, s0
	v_cvt_pk_bf16_f32 v80, v80, s0
	v_cvt_pk_bf16_f32 v64, v64, s0
	v_cvt_pk_bf16_f32 v48, v48, s0
	v_cvt_pk_bf16_f32 v32, v32, s0
	v_cvt_pk_bf16_f32 v16, v16, s0
	ds_write_b16 v190, v0 offset:28352
	v_add_f32_e32 v0, 0, v5
	ds_write_b16 v190, v112 offset:2176
	v_add_f32_e32 v112, 0, v117
	ds_write_b16 v190, v96 offset:2240
	v_add_f32_e32 v96, 0, v101
	ds_write_b16 v190, v80 offset:10880
	v_add_f32_e32 v80, 0, v85
	ds_write_b16 v190, v64 offset:10944
	v_add_f32_e32 v64, 0, v69
	ds_write_b16 v190, v48 offset:19584
	v_add_f32_e32 v48, 0, v53
	ds_write_b16 v190, v32 offset:19648
	v_add_f32_e32 v32, 0, v37
	ds_write_b16 v190, v16 offset:28288
	v_add_f32_e32 v16, 0, v21
	v_cvt_pk_bf16_f32 v0, v0, s0
	v_cvt_pk_bf16_f32 v112, v112, s0
	v_cvt_pk_bf16_f32 v96, v96, s0
	v_cvt_pk_bf16_f32 v80, v80, s0
	v_cvt_pk_bf16_f32 v64, v64, s0
	v_cvt_pk_bf16_f32 v48, v48, s0
	v_cvt_pk_bf16_f32 v32, v32, s0
	v_cvt_pk_bf16_f32 v16, v16, s0
	ds_write_b16 v190, v0 offset:28624
	v_add_f32_e32 v0, 0, v6
	ds_write_b16 v190, v112 offset:2448
	v_add_f32_e32 v112, 0, v118
	ds_write_b16 v190, v96 offset:2512
	v_add_f32_e32 v96, 0, v102
	ds_write_b16 v190, v80 offset:11152
	v_add_f32_e32 v80, 0, v86
	ds_write_b16 v190, v64 offset:11216
	v_add_f32_e32 v64, 0, v70
	ds_write_b16 v190, v48 offset:19856
	v_add_f32_e32 v48, 0, v54
	ds_write_b16 v190, v32 offset:19920
	v_add_f32_e32 v32, 0, v38
	ds_write_b16 v190, v16 offset:28560
	v_add_f32_e32 v16, 0, v22
	v_cvt_pk_bf16_f32 v0, v0, s0
	v_cvt_pk_bf16_f32 v112, v112, s0
	v_cvt_pk_bf16_f32 v96, v96, s0
	v_cvt_pk_bf16_f32 v80, v80, s0
	v_cvt_pk_bf16_f32 v64, v64, s0
	v_cvt_pk_bf16_f32 v48, v48, s0
	v_cvt_pk_bf16_f32 v32, v32, s0
	v_cvt_pk_bf16_f32 v16, v16, s0
	ds_write_b16 v190, v0 offset:28896
	v_add_f32_e32 v0, 0, v7
	ds_write_b16 v190, v112 offset:2720
	v_add_f32_e32 v112, 0, v119
	ds_write_b16 v190, v96 offset:2784
	v_add_f32_e32 v96, 0, v103
	ds_write_b16 v190, v80 offset:11424
	v_add_f32_e32 v80, 0, v87
	ds_write_b16 v190, v64 offset:11488
	v_add_f32_e32 v64, 0, v71
	ds_write_b16 v190, v48 offset:20128
	v_add_f32_e32 v48, 0, v55
	ds_write_b16 v190, v32 offset:20192
	v_add_f32_e32 v32, 0, v39
	ds_write_b16 v190, v16 offset:28832
	v_add_f32_e32 v16, 0, v23
	v_cvt_pk_bf16_f32 v0, v0, s0
	v_cvt_pk_bf16_f32 v112, v112, s0
	v_cvt_pk_bf16_f32 v96, v96, s0
	v_cvt_pk_bf16_f32 v80, v80, s0
	v_cvt_pk_bf16_f32 v64, v64, s0
	v_cvt_pk_bf16_f32 v48, v48, s0
	v_cvt_pk_bf16_f32 v32, v32, s0
	v_cvt_pk_bf16_f32 v16, v16, s0
	ds_write_b16 v190, v0 offset:29168
	v_add_f32_e32 v0, 0, v8
	ds_write_b16 v190, v112 offset:2992
	v_add_f32_e32 v112, 0, v120
	ds_write_b16 v190, v96 offset:3056
	v_add_f32_e32 v96, 0, v104
	ds_write_b16 v190, v80 offset:11696
	v_add_f32_e32 v80, 0, v88
	ds_write_b16 v190, v64 offset:11760
	v_add_f32_e32 v64, 0, v72
	ds_write_b16 v190, v48 offset:20400
	v_add_f32_e32 v48, 0, v56
	ds_write_b16 v190, v32 offset:20464
	v_add_f32_e32 v32, 0, v40
	ds_write_b16 v190, v16 offset:29104
	v_add_f32_e32 v16, 0, v24
	v_cvt_pk_bf16_f32 v0, v0, s0
	v_cvt_pk_bf16_f32 v112, v112, s0
	v_cvt_pk_bf16_f32 v96, v96, s0
	v_cvt_pk_bf16_f32 v80, v80, s0
	v_cvt_pk_bf16_f32 v64, v64, s0
	v_cvt_pk_bf16_f32 v48, v48, s0
	v_cvt_pk_bf16_f32 v32, v32, s0
	v_cvt_pk_bf16_f32 v16, v16, s0
	ds_write_b16 v190, v0 offset:30528
	v_add_f32_e32 v0, 0, v9
	ds_write_b16 v190, v112 offset:4352
	v_add_f32_e32 v112, 0, v121
	ds_write_b16 v190, v96 offset:4416
	v_add_f32_e32 v96, 0, v105
	ds_write_b16 v190, v80 offset:13056
	v_add_f32_e32 v80, 0, v89
	ds_write_b16 v190, v64 offset:13120
; DEV unsigned short f2bf(float f) { return (unsigned short)(pack2(f, 0.f) & 0xFFFFu); }
; template <int EPI>
; __device__ void gemm_phase256(const Params& P, int l, const bf16_t* __restrict__ A, const bf16_t* __restrict__ Bt, int NT, char* smem) {
;     ...
; #pragma unroll
;       for (int mi = 0; mi < 4; ++mi)
; #pragma unroll
;         for (int ni = 0; ni < 2; ++ni) {
;           const int col = wn * 64 + ni * 32 + lr;
;           const int n = n0 + col;
;           const float bias = (EPI == 0) ? ((n < NIN) ? P.b_in[l * NIN + n] : 0.f) : 0.f;
;           const int rb = wm * 128 + mi * 32 + 4 * hk;
; #pragma unroll
;           for (int i = 0; i < 16; ++i) Cs[(rb + (i & 3) + 8 * (i >> 2)) * 136 + col] = f2bf(acc[mi][ni][i] + bias);
;         }
;       __syncthreads();
	v_add_f32_e32 v64, 0, v73
	ds_write_b16 v190, v48 offset:21760
	v_add_f32_e32 v48, 0, v57
	ds_write_b16 v190, v32 offset:21824
	v_add_f32_e32 v32, 0, v41
	ds_write_b16 v190, v16 offset:30464
	v_add_f32_e32 v16, 0, v25
	v_cvt_pk_bf16_f32 v0, v0, s0
	v_cvt_pk_bf16_f32 v112, v112, s0
	v_cvt_pk_bf16_f32 v96, v96, s0
	v_cvt_pk_bf16_f32 v80, v80, s0
	v_cvt_pk_bf16_f32 v64, v64, s0
	v_cvt_pk_bf16_f32 v48, v48, s0
	v_cvt_pk_bf16_f32 v32, v32, s0
	v_cvt_pk_bf16_f32 v16, v16, s0
	ds_write_b16 v190, v0 offset:30800
	v_add_f32_e32 v0, 0, v10
	ds_write_b16 v190, v112 offset:4624
	v_add_f32_e32 v112, 0, v122
	ds_write_b16 v190, v96 offset:4688
	v_add_f32_e32 v96, 0, v106
	ds_write_b16 v190, v80 offset:13328
	v_add_f32_e32 v80, 0, v90
	ds_write_b16 v190, v64 offset:13392
	v_add_f32_e32 v64, 0, v74
	ds_write_b16 v190, v48 offset:22032
	v_add_f32_e32 v48, 0, v58
	ds_write_b16 v190, v32 offset:22096
	v_add_f32_e32 v32, 0, v42
	ds_write_b16 v190, v16 offset:30736
	v_add_f32_e32 v16, 0, v26
	v_cvt_pk_bf16_f32 v0, v0, s0
	v_cvt_pk_bf16_f32 v112, v112, s0
	v_cvt_pk_bf16_f32 v96, v96, s0
	v_cvt_pk_bf16_f32 v80, v80, s0
	v_cvt_pk_bf16_f32 v64, v64, s0
	v_cvt_pk_bf16_f32 v48, v48, s0
	v_cvt_pk_bf16_f32 v32, v32, s0
	v_cvt_pk_bf16_f32 v16, v16, s0
	ds_write_b16 v190, v0 offset:31072
	v_add_f32_e32 v0, 0, v11
	ds_write_b16 v190, v112 offset:4896
	v_add_f32_e32 v112, 0, v123
	ds_write_b16 v190, v96 offset:4960
	v_add_f32_e32 v96, 0, v107
	ds_write_b16 v190, v80 offset:13600
	v_add_f32_e32 v80, 0, v91
	ds_write_b16 v190, v64 offset:13664
	v_add_f32_e32 v64, 0, v75
	ds_write_b16 v190, v48 offset:22304
	v_add_f32_e32 v48, 0, v59
	ds_write_b16 v190, v32 offset:22368
	v_add_f32_e32 v32, 0, v43
	ds_write_b16 v190, v16 offset:31008
	v_add_f32_e32 v16, 0, v27
	v_cvt_pk_bf16_f32 v0, v0, s0
	v_cvt_pk_bf16_f32 v112, v112, s0
	v_cvt_pk_bf16_f32 v96, v96, s0
	v_cvt_pk_bf16_f32 v80, v80, s0
	v_cvt_pk_bf16_f32 v64, v64, s0
	v_cvt_pk_bf16_f32 v48, v48, s0
	v_cvt_pk_bf16_f32 v32, v32, s0
	v_cvt_pk_bf16_f32 v16, v16, s0
	ds_write_b16 v190, v0 offset:31344
	v_add_f32_e32 v0, 0, v12
	ds_write_b16 v190, v112 offset:5168
	v_add_f32_e32 v112, 0, v124
	ds_write_b16 v190, v96 offset:5232
	v_add_f32_e32 v96, 0, v108
	ds_write_b16 v190, v80 offset:13872
	v_add_f32_e32 v80, 0, v92
	ds_write_b16 v190, v64 offset:13936
	v_add_f32_e32 v64, 0, v76
	ds_write_b16 v190, v48 offset:22576
	v_add_f32_e32 v48, 0, v60
	ds_write_b16 v190, v32 offset:22640
	v_add_f32_e32 v32, 0, v44
	ds_write_b16 v190, v16 offset:31280
	v_add_f32_e32 v16, 0, v28
	v_cvt_pk_bf16_f32 v0, v0, s0
	v_cvt_pk_bf16_f32 v112, v112, s0
	v_cvt_pk_bf16_f32 v96, v96, s0
	v_cvt_pk_bf16_f32 v80, v80, s0
	v_cvt_pk_bf16_f32 v64, v64, s0
	v_cvt_pk_bf16_f32 v48, v48, s0
	v_cvt_pk_bf16_f32 v32, v32, s0
	v_cvt_pk_bf16_f32 v16, v16, s0
	ds_write_b16 v190, v0 offset:32704
	v_add_f32_e32 v0, 0, v13
	ds_write_b16 v190, v112 offset:6528
	v_add_f32_e32 v112, 0, v125
	ds_write_b16 v190, v96 offset:6592
	v_add_f32_e32 v96, 0, v109
	ds_write_b16 v190, v80 offset:15232
	v_add_f32_e32 v80, 0, v93
	ds_write_b16 v190, v64 offset:15296
	v_add_f32_e32 v64, 0, v77
	ds_write_b16 v190, v48 offset:23936
	v_add_f32_e32 v48, 0, v61
	ds_write_b16 v190, v32 offset:24000
	v_add_f32_e32 v32, 0, v45
	ds_write_b16 v190, v16 offset:32640
	v_add_f32_e32 v16, 0, v29
	v_cvt_pk_bf16_f32 v0, v0, s0
	v_cvt_pk_bf16_f32 v112, v112, s0
	v_cvt_pk_bf16_f32 v96, v96, s0
	v_cvt_pk_bf16_f32 v80, v80, s0
	v_cvt_pk_bf16_f32 v64, v64, s0
	v_cvt_pk_bf16_f32 v48, v48, s0
	v_cvt_pk_bf16_f32 v32, v32, s0
	v_cvt_pk_bf16_f32 v16, v16, s0
	ds_write_b16 v190, v0 offset:32976
	v_add_f32_e32 v0, 0, v14
	ds_write_b16 v190, v112 offset:6800
	v_add_f32_e32 v112, 0, v126
	ds_write_b16 v190, v96 offset:6864
	v_add_f32_e32 v96, 0, v110
	ds_write_b16 v190, v80 offset:15504
	v_add_f32_e32 v80, 0, v94
	ds_write_b16 v190, v64 offset:15568
	v_add_f32_e32 v64, 0, v78
	ds_write_b16 v190, v48 offset:24208
	v_add_f32_e32 v48, 0, v62
	ds_write_b16 v190, v32 offset:24272
	v_add_f32_e32 v32, 0, v46
	ds_write_b16 v190, v16 offset:32912
	v_add_f32_e32 v16, 0, v30
	v_cvt_pk_bf16_f32 v0, v0, s0
	v_cvt_pk_bf16_f32 v112, v112, s0
	v_cvt_pk_bf16_f32 v96, v96, s0
	v_cvt_pk_bf16_f32 v80, v80, s0
	v_cvt_pk_bf16_f32 v64, v64, s0
	v_cvt_pk_bf16_f32 v48, v48, s0
	v_cvt_pk_bf16_f32 v32, v32, s0
	v_cvt_pk_bf16_f32 v16, v16, s0
	ds_write_b16 v190, v0 offset:33248
	v_add_f32_e32 v0, 0, v15
	ds_write_b16 v190, v112 offset:7072
	v_add_f32_e32 v112, 0, v127
	ds_write_b16 v190, v96 offset:7136
	v_add_f32_e32 v96, 0, v111
	ds_write_b16 v190, v80 offset:15776
	v_add_f32_e32 v80, 0, v95
	ds_write_b16 v190, v64 offset:15840
	v_add_f32_e32 v64, 0, v79
	ds_write_b16 v190, v48 offset:24480
	v_add_f32_e32 v48, 0, v63
	ds_write_b16 v190, v32 offset:24544
	v_add_f32_e32 v32, 0, v47
	ds_write_b16 v190, v16 offset:33184
	v_add_f32_e32 v16, 0, v31
	v_cvt_pk_bf16_f32 v0, v0, s0
	v_cvt_pk_bf16_f32 v112, v112, s0
	v_cvt_pk_bf16_f32 v96, v96, s0
	v_cvt_pk_bf16_f32 v80, v80, s0
	v_cvt_pk_bf16_f32 v64, v64, s0
	v_cvt_pk_bf16_f32 v48, v48, s0
	v_cvt_pk_bf16_f32 v32, v32, s0
	v_cvt_pk_bf16_f32 v16, v16, s0
	ds_write_b16 v190, v0 offset:33520
	v_lshl_add_u64 v[0:1], s[0:1], 1, v[192:193]
	s_mov_b32 s0, 0
	ds_write_b16 v190, v112 offset:7344
	ds_write_b16 v190, v96 offset:7408
	ds_write_b16 v190, v80 offset:16048
	ds_write_b16 v190, v64 offset:16112
	ds_write_b16 v190, v48 offset:24752
	ds_write_b16 v190, v32 offset:24816
	ds_write_b16 v190, v16 offset:33456
	s_waitcnt lgkmcnt(0)
	s_barrier
